# RG in-proj activation epilogue (identity | gelu_tanh) rewritten with packed f32 operations (same arithmetic, 36% fewer instructions on gelu tiles)
# speedup vs baseline: 1.0127x; 1.0012x over previous
.LBB0_858:
	s_lshl_b32 s90, s46, 11
	s_add_i32 s90, s90, 0x20400
	s_lshl_b32 s91, s38, 2
	s_add_i32 s91, s90, s91
	v_lshl_add_u32 v181, v182, 2, s91
	ds_read_b32 v180, v181 offset:0
	ds_read_b32 v188, v181 offset:64
	ds_read_b32 v190, v181 offset:128
	ds_read_b32 v192, v181 offset:192
	ds_read_b32 v194, v181 offset:512
	ds_read_b32 v196, v181 offset:576
	ds_read_b32 v210, v181 offset:640
	ds_read_b32 v212, v181 offset:704
	s_lshl_b32 s91, s39, 2
	s_add_i32 s91, s90, s91
	v_lshl_add_u32 v181, v184, 2, s91
	ds_read_b128 v[42:45], v181 offset:1024
	ds_read_b128 v[46:49], v181 offset:1040
	ds_read_b128 v[58:61], v181 offset:1536
	ds_read_b128 v[62:65], v181 offset:1552
	v_lshl_or_b32 v189, s44, 8, v186
	v_lshl_add_u32 v181, s45, 8, v183
	v_lshlrev_b32_e32 v181, 13, v181
	v_lshl_add_u32 v189, v189, 1, v181
	s_mov_b32 s84, 0x3d372713
	s_mov_b32 s86, 0x3fcc422a
	s_mov_b32 s88, 0xbfb8aa3b
	s_and_b32 s16, s44, -4
	v_readlane_b32 s48, v244, 61
	v_readlane_b32 s49, v244, 62
	s_cmp_lg_u32 s16, 4
	s_cbranch_scc1 .Lact0_rgin_id
	s_waitcnt lgkmcnt(0)
	s_add_u32 s80, s10, 0x0
	s_addc_u32 s81, s11, 0
	v_pk_fma_f32 v[142:143], v[142:143], v[180:181], v[42:43] op_sel_hi:[1,0,1]
	v_pk_fma_f32 v[144:145], v[144:145], v[180:181], v[44:45] op_sel_hi:[1,0,1]
	v_pk_fma_f32 v[138:139], v[138:139], v[180:181], v[46:47] op_sel_hi:[1,0,1]
	v_pk_fma_f32 v[140:141], v[140:141], v[180:181], v[48:49] op_sel_hi:[1,0,1]
	v_pk_mul_f32 v[172:173], v[142:143], s[84:85] op_sel_hi:[1,0]
	v_pk_mul_f32 v[174:175], v[144:145], s[84:85] op_sel_hi:[1,0]
	v_pk_mul_f32 v[176:177], v[138:139], s[84:85] op_sel_hi:[1,0]
	v_pk_mul_f32 v[178:179], v[140:141], s[84:85] op_sel_hi:[1,0]
	v_pk_mul_f32 v[172:173], v[142:143], v[172:173]
	v_pk_mul_f32 v[174:175], v[144:145], v[174:175]
	v_pk_mul_f32 v[176:177], v[138:139], v[176:177]
	v_pk_mul_f32 v[178:179], v[140:141], v[178:179]
	v_pk_fma_f32 v[172:173], v[142:143], v[172:173], v[142:143]
	v_pk_fma_f32 v[174:175], v[144:145], v[174:175], v[144:145]
	v_pk_fma_f32 v[176:177], v[138:139], v[176:177], v[138:139]
	v_pk_fma_f32 v[178:179], v[140:141], v[178:179], v[140:141]
	v_pk_mul_f32 v[172:173], v[172:173], s[86:87] op_sel_hi:[1,0]
	v_pk_mul_f32 v[174:175], v[174:175], s[86:87] op_sel_hi:[1,0]
	v_pk_mul_f32 v[176:177], v[176:177], s[86:87] op_sel_hi:[1,0]
	v_pk_mul_f32 v[178:179], v[178:179], s[86:87] op_sel_hi:[1,0]
	v_pk_mul_f32 v[172:173], v[172:173], s[88:89] op_sel_hi:[1,0]
	v_pk_mul_f32 v[174:175], v[174:175], s[88:89] op_sel_hi:[1,0]
	v_pk_mul_f32 v[176:177], v[176:177], s[88:89] op_sel_hi:[1,0]
	v_pk_mul_f32 v[178:179], v[178:179], s[88:89] op_sel_hi:[1,0]
	v_exp_f32_e32 v172, v172
	v_exp_f32_e32 v173, v173
	v_exp_f32_e32 v174, v174
	v_exp_f32_e32 v175, v175
	v_exp_f32_e32 v176, v176
	v_exp_f32_e32 v177, v177
	v_exp_f32_e32 v178, v178
	v_exp_f32_e32 v179, v179
	v_pk_add_f32 v[172:173], v[172:173], 1.0 op_sel_hi:[1,0]
	v_pk_add_f32 v[174:175], v[174:175], 1.0 op_sel_hi:[1,0]
	v_pk_add_f32 v[176:177], v[176:177], 1.0 op_sel_hi:[1,0]
	v_pk_add_f32 v[178:179], v[178:179], 1.0 op_sel_hi:[1,0]
	v_rcp_f32_e32 v172, v172
	v_rcp_f32_e32 v173, v173
	v_rcp_f32_e32 v174, v174
	v_rcp_f32_e32 v175, v175
	v_rcp_f32_e32 v176, v176
	v_rcp_f32_e32 v177, v177
	v_rcp_f32_e32 v178, v178
	v_rcp_f32_e32 v179, v179
	v_pk_mul_f32 v[142:143], v[142:143], v[172:173]
	v_pk_mul_f32 v[144:145], v[144:145], v[174:175]
	v_pk_mul_f32 v[138:139], v[138:139], v[176:177]
	v_pk_mul_f32 v[140:141], v[140:141], v[178:179]
	v_cvt_pk_bf16_f32 v168, v142, v143
	v_cvt_pk_bf16_f32 v169, v144, v145
	v_cvt_pk_bf16_f32 v170, v138, v139
	v_cvt_pk_bf16_f32 v171, v140, v141
	global_store_dwordx4 v189, v[168:171], s[80:81]
	v_pk_fma_f32 v[134:135], v[134:135], v[180:181], v[58:59] op_sel_hi:[1,0,1]
	v_pk_fma_f32 v[136:137], v[136:137], v[180:181], v[60:61] op_sel_hi:[1,0,1]
	v_pk_fma_f32 v[130:131], v[130:131], v[180:181], v[62:63] op_sel_hi:[1,0,1]
	v_pk_fma_f32 v[132:133], v[132:133], v[180:181], v[64:65] op_sel_hi:[1,0,1]
	v_pk_mul_f32 v[172:173], v[134:135], s[84:85] op_sel_hi:[1,0]
	v_pk_mul_f32 v[174:175], v[136:137], s[84:85] op_sel_hi:[1,0]
	v_pk_mul_f32 v[176:177], v[130:131], s[84:85] op_sel_hi:[1,0]
	v_pk_mul_f32 v[178:179], v[132:133], s[84:85] op_sel_hi:[1,0]
	v_pk_mul_f32 v[172:173], v[134:135], v[172:173]
	v_pk_mul_f32 v[174:175], v[136:137], v[174:175]
	v_pk_mul_f32 v[176:177], v[130:131], v[176:177]
	v_pk_mul_f32 v[178:179], v[132:133], v[178:179]
	v_pk_fma_f32 v[172:173], v[134:135], v[172:173], v[134:135]
	v_pk_fma_f32 v[174:175], v[136:137], v[174:175], v[136:137]
	v_pk_fma_f32 v[176:177], v[130:131], v[176:177], v[130:131]
	v_pk_fma_f32 v[178:179], v[132:133], v[178:179], v[132:133]
	v_pk_mul_f32 v[172:173], v[172:173], s[86:87] op_sel_hi:[1,0]
	v_pk_mul_f32 v[174:175], v[174:175], s[86:87] op_sel_hi:[1,0]
	v_pk_mul_f32 v[176:177], v[176:177], s[86:87] op_sel_hi:[1,0]
	v_pk_mul_f32 v[178:179], v[178:179], s[86:87] op_sel_hi:[1,0]
	v_pk_mul_f32 v[172:173], v[172:173], s[88:89] op_sel_hi:[1,0]
	v_pk_mul_f32 v[174:175], v[174:175], s[88:89] op_sel_hi:[1,0]
	v_pk_mul_f32 v[176:177], v[176:177], s[88:89] op_sel_hi:[1,0]
	v_pk_mul_f32 v[178:179], v[178:179], s[88:89] op_sel_hi:[1,0]
	v_exp_f32_e32 v172, v172
	v_exp_f32_e32 v173, v173
	v_exp_f32_e32 v174, v174
	v_exp_f32_e32 v175, v175
	v_exp_f32_e32 v176, v176
	v_exp_f32_e32 v177, v177
	v_exp_f32_e32 v178, v178
	v_exp_f32_e32 v179, v179
	v_pk_add_f32 v[172:173], v[172:173], 1.0 op_sel_hi:[1,0]
	v_pk_add_f32 v[174:175], v[174:175], 1.0 op_sel_hi:[1,0]
	v_pk_add_f32 v[176:177], v[176:177], 1.0 op_sel_hi:[1,0]
	v_pk_add_f32 v[178:179], v[178:179], 1.0 op_sel_hi:[1,0]
	v_rcp_f32_e32 v172, v172
	v_rcp_f32_e32 v173, v173
	v_rcp_f32_e32 v174, v174
	v_rcp_f32_e32 v175, v175
	v_rcp_f32_e32 v176, v176
	v_rcp_f32_e32 v177, v177
	v_rcp_f32_e32 v178, v178
	v_rcp_f32_e32 v179, v179
	v_pk_mul_f32 v[134:135], v[134:135], v[172:173]
	v_pk_mul_f32 v[136:137], v[136:137], v[174:175]
	v_pk_mul_f32 v[130:131], v[130:131], v[176:177]
	v_pk_mul_f32 v[132:133], v[132:133], v[178:179]
	s_nop 0
	v_cvt_pk_bf16_f32 v168, v134, v135
	v_cvt_pk_bf16_f32 v169, v136, v137
	v_cvt_pk_bf16_f32 v170, v130, v131
	v_cvt_pk_bf16_f32 v171, v132, v133
	global_store_dwordx4 v189, v[168:171], s[80:81] offset:256
	s_add_u32 s80, s10, 0x20000
	s_addc_u32 s81, s11, 0
	v_pk_fma_f32 v[126:127], v[126:127], v[188:189], v[42:43] op_sel_hi:[1,0,1]
	v_pk_fma_f32 v[128:129], v[128:129], v[188:189], v[44:45] op_sel_hi:[1,0,1]
	v_pk_fma_f32 v[122:123], v[122:123], v[188:189], v[46:47] op_sel_hi:[1,0,1]
	v_pk_fma_f32 v[124:125], v[124:125], v[188:189], v[48:49] op_sel_hi:[1,0,1]
	v_pk_mul_f32 v[172:173], v[126:127], s[84:85] op_sel_hi:[1,0]
	v_pk_mul_f32 v[174:175], v[128:129], s[84:85] op_sel_hi:[1,0]
	v_pk_mul_f32 v[176:177], v[122:123], s[84:85] op_sel_hi:[1,0]
	v_pk_mul_f32 v[178:179], v[124:125], s[84:85] op_sel_hi:[1,0]
	v_pk_mul_f32 v[172:173], v[126:127], v[172:173]
	v_pk_mul_f32 v[174:175], v[128:129], v[174:175]
	v_pk_mul_f32 v[176:177], v[122:123], v[176:177]
	v_pk_mul_f32 v[178:179], v[124:125], v[178:179]
	v_pk_fma_f32 v[172:173], v[126:127], v[172:173], v[126:127]
	v_pk_fma_f32 v[174:175], v[128:129], v[174:175], v[128:129]
	v_pk_fma_f32 v[176:177], v[122:123], v[176:177], v[122:123]
	v_pk_fma_f32 v[178:179], v[124:125], v[178:179], v[124:125]
	v_pk_mul_f32 v[172:173], v[172:173], s[86:87] op_sel_hi:[1,0]
	v_pk_mul_f32 v[174:175], v[174:175], s[86:87] op_sel_hi:[1,0]
	v_pk_mul_f32 v[176:177], v[176:177], s[86:87] op_sel_hi:[1,0]
	v_pk_mul_f32 v[178:179], v[178:179], s[86:87] op_sel_hi:[1,0]
	v_pk_mul_f32 v[172:173], v[172:173], s[88:89] op_sel_hi:[1,0]
	v_pk_mul_f32 v[174:175], v[174:175], s[88:89] op_sel_hi:[1,0]
	v_pk_mul_f32 v[176:177], v[176:177], s[88:89] op_sel_hi:[1,0]
	v_pk_mul_f32 v[178:179], v[178:179], s[88:89] op_sel_hi:[1,0]
	v_exp_f32_e32 v172, v172
	v_exp_f32_e32 v173, v173
	v_exp_f32_e32 v174, v174
	v_exp_f32_e32 v175, v175
	v_exp_f32_e32 v176, v176
	v_exp_f32_e32 v177, v177
	v_exp_f32_e32 v178, v178
	v_exp_f32_e32 v179, v179
	v_pk_add_f32 v[172:173], v[172:173], 1.0 op_sel_hi:[1,0]
	v_pk_add_f32 v[174:175], v[174:175], 1.0 op_sel_hi:[1,0]
	v_pk_add_f32 v[176:177], v[176:177], 1.0 op_sel_hi:[1,0]
	v_pk_add_f32 v[178:179], v[178:179], 1.0 op_sel_hi:[1,0]
	v_rcp_f32_e32 v172, v172
	v_rcp_f32_e32 v173, v173
	v_rcp_f32_e32 v174, v174
	v_rcp_f32_e32 v175, v175
	v_rcp_f32_e32 v176, v176
	v_rcp_f32_e32 v177, v177
	v_rcp_f32_e32 v178, v178
	v_rcp_f32_e32 v179, v179
	v_pk_mul_f32 v[126:127], v[126:127], v[172:173]
	v_pk_mul_f32 v[128:129], v[128:129], v[174:175]
	v_pk_mul_f32 v[122:123], v[122:123], v[176:177]
	v_pk_mul_f32 v[124:125], v[124:125], v[178:179]
	v_cvt_pk_bf16_f32 v168, v126, v127
	v_cvt_pk_bf16_f32 v169, v128, v129
	v_cvt_pk_bf16_f32 v170, v122, v123
	v_cvt_pk_bf16_f32 v171, v124, v125
	global_store_dwordx4 v189, v[168:171], s[80:81]
	v_pk_fma_f32 v[118:119], v[118:119], v[188:189], v[58:59] op_sel_hi:[1,0,1]
	v_pk_fma_f32 v[120:121], v[120:121], v[188:189], v[60:61] op_sel_hi:[1,0,1]
	v_pk_fma_f32 v[114:115], v[114:115], v[188:189], v[62:63] op_sel_hi:[1,0,1]
	v_pk_fma_f32 v[116:117], v[116:117], v[188:189], v[64:65] op_sel_hi:[1,0,1]
	v_pk_mul_f32 v[172:173], v[118:119], s[84:85] op_sel_hi:[1,0]
	v_pk_mul_f32 v[174:175], v[120:121], s[84:85] op_sel_hi:[1,0]
	v_pk_mul_f32 v[176:177], v[114:115], s[84:85] op_sel_hi:[1,0]
	v_pk_mul_f32 v[178:179], v[116:117], s[84:85] op_sel_hi:[1,0]
	v_pk_mul_f32 v[172:173], v[118:119], v[172:173]
	v_pk_mul_f32 v[174:175], v[120:121], v[174:175]
	v_pk_mul_f32 v[176:177], v[114:115], v[176:177]
	v_pk_mul_f32 v[178:179], v[116:117], v[178:179]
	v_pk_fma_f32 v[172:173], v[118:119], v[172:173], v[118:119]
	v_pk_fma_f32 v[174:175], v[120:121], v[174:175], v[120:121]
	v_pk_fma_f32 v[176:177], v[114:115], v[176:177], v[114:115]
	v_pk_fma_f32 v[178:179], v[116:117], v[178:179], v[116:117]
	v_pk_mul_f32 v[172:173], v[172:173], s[86:87] op_sel_hi:[1,0]
	v_pk_mul_f32 v[174:175], v[174:175], s[86:87] op_sel_hi:[1,0]
	v_pk_mul_f32 v[176:177], v[176:177], s[86:87] op_sel_hi:[1,0]
	v_pk_mul_f32 v[178:179], v[178:179], s[86:87] op_sel_hi:[1,0]
	v_pk_mul_f32 v[172:173], v[172:173], s[88:89] op_sel_hi:[1,0]
	v_pk_mul_f32 v[174:175], v[174:175], s[88:89] op_sel_hi:[1,0]
	v_pk_mul_f32 v[176:177], v[176:177], s[88:89] op_sel_hi:[1,0]
	v_pk_mul_f32 v[178:179], v[178:179], s[88:89] op_sel_hi:[1,0]
	v_exp_f32_e32 v172, v172
	v_exp_f32_e32 v173, v173
	v_exp_f32_e32 v174, v174
	v_exp_f32_e32 v175, v175
	v_exp_f32_e32 v176, v176
	v_exp_f32_e32 v177, v177
	v_exp_f32_e32 v178, v178
	v_exp_f32_e32 v179, v179
	v_pk_add_f32 v[172:173], v[172:173], 1.0 op_sel_hi:[1,0]
	v_pk_add_f32 v[174:175], v[174:175], 1.0 op_sel_hi:[1,0]
	v_pk_add_f32 v[176:177], v[176:177], 1.0 op_sel_hi:[1,0]
	v_pk_add_f32 v[178:179], v[178:179], 1.0 op_sel_hi:[1,0]
	v_rcp_f32_e32 v172, v172
	v_rcp_f32_e32 v173, v173
	v_rcp_f32_e32 v174, v174
	v_rcp_f32_e32 v175, v175
	v_rcp_f32_e32 v176, v176
	v_rcp_f32_e32 v177, v177
	v_rcp_f32_e32 v178, v178
	v_rcp_f32_e32 v179, v179
	v_pk_mul_f32 v[118:119], v[118:119], v[172:173]
	v_pk_mul_f32 v[120:121], v[120:121], v[174:175]
	v_pk_mul_f32 v[114:115], v[114:115], v[176:177]
	v_pk_mul_f32 v[116:117], v[116:117], v[178:179]
	s_nop 0
	v_cvt_pk_bf16_f32 v168, v118, v119
	v_cvt_pk_bf16_f32 v169, v120, v121
	v_cvt_pk_bf16_f32 v170, v114, v115
	v_cvt_pk_bf16_f32 v171, v116, v117
	global_store_dwordx4 v189, v[168:171], s[80:81] offset:256
	s_add_u32 s80, s10, 0x40000
	s_addc_u32 s81, s11, 0
	v_pk_fma_f32 v[110:111], v[110:111], v[190:191], v[42:43] op_sel_hi:[1,0,1]
	v_pk_fma_f32 v[112:113], v[112:113], v[190:191], v[44:45] op_sel_hi:[1,0,1]
	v_pk_fma_f32 v[106:107], v[106:107], v[190:191], v[46:47] op_sel_hi:[1,0,1]
	v_pk_fma_f32 v[108:109], v[108:109], v[190:191], v[48:49] op_sel_hi:[1,0,1]
	v_pk_mul_f32 v[172:173], v[110:111], s[84:85] op_sel_hi:[1,0]
	v_pk_mul_f32 v[174:175], v[112:113], s[84:85] op_sel_hi:[1,0]
	v_pk_mul_f32 v[176:177], v[106:107], s[84:85] op_sel_hi:[1,0]
	v_pk_mul_f32 v[178:179], v[108:109], s[84:85] op_sel_hi:[1,0]
	v_pk_mul_f32 v[172:173], v[110:111], v[172:173]
	v_pk_mul_f32 v[174:175], v[112:113], v[174:175]
	v_pk_mul_f32 v[176:177], v[106:107], v[176:177]
	v_pk_mul_f32 v[178:179], v[108:109], v[178:179]
	v_pk_fma_f32 v[172:173], v[110:111], v[172:173], v[110:111]
	v_pk_fma_f32 v[174:175], v[112:113], v[174:175], v[112:113]
	v_pk_fma_f32 v[176:177], v[106:107], v[176:177], v[106:107]
	v_pk_fma_f32 v[178:179], v[108:109], v[178:179], v[108:109]
	v_pk_mul_f32 v[172:173], v[172:173], s[86:87] op_sel_hi:[1,0]
	v_pk_mul_f32 v[174:175], v[174:175], s[86:87] op_sel_hi:[1,0]
	v_pk_mul_f32 v[176:177], v[176:177], s[86:87] op_sel_hi:[1,0]
	v_pk_mul_f32 v[178:179], v[178:179], s[86:87] op_sel_hi:[1,0]
	v_pk_mul_f32 v[172:173], v[172:173], s[88:89] op_sel_hi:[1,0]
	v_pk_mul_f32 v[174:175], v[174:175], s[88:89] op_sel_hi:[1,0]
	v_pk_mul_f32 v[176:177], v[176:177], s[88:89] op_sel_hi:[1,0]
	v_pk_mul_f32 v[178:179], v[178:179], s[88:89] op_sel_hi:[1,0]
	v_exp_f32_e32 v172, v172
	v_exp_f32_e32 v173, v173
	v_exp_f32_e32 v174, v174
	v_exp_f32_e32 v175, v175
	v_exp_f32_e32 v176, v176
	v_exp_f32_e32 v177, v177
	v_exp_f32_e32 v178, v178
	v_exp_f32_e32 v179, v179
	v_pk_add_f32 v[172:173], v[172:173], 1.0 op_sel_hi:[1,0]
	v_pk_add_f32 v[174:175], v[174:175], 1.0 op_sel_hi:[1,0]
	v_pk_add_f32 v[176:177], v[176:177], 1.0 op_sel_hi:[1,0]
	v_pk_add_f32 v[178:179], v[178:179], 1.0 op_sel_hi:[1,0]
	v_rcp_f32_e32 v172, v172
	v_rcp_f32_e32 v173, v173
	v_rcp_f32_e32 v174, v174
	v_rcp_f32_e32 v175, v175
	v_rcp_f32_e32 v176, v176
	v_rcp_f32_e32 v177, v177
	v_rcp_f32_e32 v178, v178
	v_rcp_f32_e32 v179, v179
	v_pk_mul_f32 v[110:111], v[110:111], v[172:173]
	v_pk_mul_f32 v[112:113], v[112:113], v[174:175]
	v_pk_mul_f32 v[106:107], v[106:107], v[176:177]
	v_pk_mul_f32 v[108:109], v[108:109], v[178:179]
	v_cvt_pk_bf16_f32 v168, v110, v111
	v_cvt_pk_bf16_f32 v169, v112, v113
	v_cvt_pk_bf16_f32 v170, v106, v107
	v_cvt_pk_bf16_f32 v171, v108, v109
	global_store_dwordx4 v189, v[168:171], s[80:81]
	v_pk_fma_f32 v[102:103], v[102:103], v[190:191], v[58:59] op_sel_hi:[1,0,1]
	v_pk_fma_f32 v[104:105], v[104:105], v[190:191], v[60:61] op_sel_hi:[1,0,1]
	v_pk_fma_f32 v[98:99], v[98:99], v[190:191], v[62:63] op_sel_hi:[1,0,1]
	v_pk_fma_f32 v[100:101], v[100:101], v[190:191], v[64:65] op_sel_hi:[1,0,1]
	v_pk_mul_f32 v[172:173], v[102:103], s[84:85] op_sel_hi:[1,0]
	v_pk_mul_f32 v[174:175], v[104:105], s[84:85] op_sel_hi:[1,0]
	v_pk_mul_f32 v[176:177], v[98:99], s[84:85] op_sel_hi:[1,0]
	v_pk_mul_f32 v[178:179], v[100:101], s[84:85] op_sel_hi:[1,0]
	v_pk_mul_f32 v[172:173], v[102:103], v[172:173]
	v_pk_mul_f32 v[174:175], v[104:105], v[174:175]
	v_pk_mul_f32 v[176:177], v[98:99], v[176:177]
	v_pk_mul_f32 v[178:179], v[100:101], v[178:179]
	v_pk_fma_f32 v[172:173], v[102:103], v[172:173], v[102:103]
	v_pk_fma_f32 v[174:175], v[104:105], v[174:175], v[104:105]
	v_pk_fma_f32 v[176:177], v[98:99], v[176:177], v[98:99]
	v_pk_fma_f32 v[178:179], v[100:101], v[178:179], v[100:101]
	v_pk_mul_f32 v[172:173], v[172:173], s[86:87] op_sel_hi:[1,0]
	v_pk_mul_f32 v[174:175], v[174:175], s[86:87] op_sel_hi:[1,0]
	v_pk_mul_f32 v[176:177], v[176:177], s[86:87] op_sel_hi:[1,0]
	v_pk_mul_f32 v[178:179], v[178:179], s[86:87] op_sel_hi:[1,0]
	v_pk_mul_f32 v[172:173], v[172:173], s[88:89] op_sel_hi:[1,0]
	v_pk_mul_f32 v[174:175], v[174:175], s[88:89] op_sel_hi:[1,0]
	v_pk_mul_f32 v[176:177], v[176:177], s[88:89] op_sel_hi:[1,0]
	v_pk_mul_f32 v[178:179], v[178:179], s[88:89] op_sel_hi:[1,0]
	v_exp_f32_e32 v172, v172
	v_exp_f32_e32 v173, v173
	v_exp_f32_e32 v174, v174
	v_exp_f32_e32 v175, v175
	v_exp_f32_e32 v176, v176
	v_exp_f32_e32 v177, v177
	v_exp_f32_e32 v178, v178
	v_exp_f32_e32 v179, v179
	v_pk_add_f32 v[172:173], v[172:173], 1.0 op_sel_hi:[1,0]
	v_pk_add_f32 v[174:175], v[174:175], 1.0 op_sel_hi:[1,0]
	v_pk_add_f32 v[176:177], v[176:177], 1.0 op_sel_hi:[1,0]
	v_pk_add_f32 v[178:179], v[178:179], 1.0 op_sel_hi:[1,0]
	v_rcp_f32_e32 v172, v172
	v_rcp_f32_e32 v173, v173
	v_rcp_f32_e32 v174, v174
	v_rcp_f32_e32 v175, v175
	v_rcp_f32_e32 v176, v176
	v_rcp_f32_e32 v177, v177
	v_rcp_f32_e32 v178, v178
	v_rcp_f32_e32 v179, v179
	v_pk_mul_f32 v[102:103], v[102:103], v[172:173]
	v_pk_mul_f32 v[104:105], v[104:105], v[174:175]
	v_pk_mul_f32 v[98:99], v[98:99], v[176:177]
	v_pk_mul_f32 v[100:101], v[100:101], v[178:179]
	s_nop 0
	v_cvt_pk_bf16_f32 v168, v102, v103
	v_cvt_pk_bf16_f32 v169, v104, v105
	v_cvt_pk_bf16_f32 v170, v98, v99
	v_cvt_pk_bf16_f32 v171, v100, v101
	global_store_dwordx4 v189, v[168:171], s[80:81] offset:256
	s_add_u32 s80, s10, 0x60000
	s_addc_u32 s81, s11, 0
	v_pk_fma_f32 v[94:95], v[94:95], v[192:193], v[42:43] op_sel_hi:[1,0,1]
	v_pk_fma_f32 v[96:97], v[96:97], v[192:193], v[44:45] op_sel_hi:[1,0,1]
	v_pk_fma_f32 v[90:91], v[90:91], v[192:193], v[46:47] op_sel_hi:[1,0,1]
	v_pk_fma_f32 v[92:93], v[92:93], v[192:193], v[48:49] op_sel_hi:[1,0,1]
	v_pk_mul_f32 v[172:173], v[94:95], s[84:85] op_sel_hi:[1,0]
	v_pk_mul_f32 v[174:175], v[96:97], s[84:85] op_sel_hi:[1,0]
	v_pk_mul_f32 v[176:177], v[90:91], s[84:85] op_sel_hi:[1,0]
	v_pk_mul_f32 v[178:179], v[92:93], s[84:85] op_sel_hi:[1,0]
	v_pk_mul_f32 v[172:173], v[94:95], v[172:173]
	v_pk_mul_f32 v[174:175], v[96:97], v[174:175]
	v_pk_mul_f32 v[176:177], v[90:91], v[176:177]
	v_pk_mul_f32 v[178:179], v[92:93], v[178:179]
	v_pk_fma_f32 v[172:173], v[94:95], v[172:173], v[94:95]
	v_pk_fma_f32 v[174:175], v[96:97], v[174:175], v[96:97]
	v_pk_fma_f32 v[176:177], v[90:91], v[176:177], v[90:91]
	v_pk_fma_f32 v[178:179], v[92:93], v[178:179], v[92:93]
	v_pk_mul_f32 v[172:173], v[172:173], s[86:87] op_sel_hi:[1,0]
	v_pk_mul_f32 v[174:175], v[174:175], s[86:87] op_sel_hi:[1,0]
	v_pk_mul_f32 v[176:177], v[176:177], s[86:87] op_sel_hi:[1,0]
	v_pk_mul_f32 v[178:179], v[178:179], s[86:87] op_sel_hi:[1,0]
	v_pk_mul_f32 v[172:173], v[172:173], s[88:89] op_sel_hi:[1,0]
	v_pk_mul_f32 v[174:175], v[174:175], s[88:89] op_sel_hi:[1,0]
	v_pk_mul_f32 v[176:177], v[176:177], s[88:89] op_sel_hi:[1,0]
	v_pk_mul_f32 v[178:179], v[178:179], s[88:89] op_sel_hi:[1,0]
	v_exp_f32_e32 v172, v172
	v_exp_f32_e32 v173, v173
	v_exp_f32_e32 v174, v174
	v_exp_f32_e32 v175, v175
	v_exp_f32_e32 v176, v176
	v_exp_f32_e32 v177, v177
	v_exp_f32_e32 v178, v178
	v_exp_f32_e32 v179, v179
	v_pk_add_f32 v[172:173], v[172:173], 1.0 op_sel_hi:[1,0]
	v_pk_add_f32 v[174:175], v[174:175], 1.0 op_sel_hi:[1,0]
	v_pk_add_f32 v[176:177], v[176:177], 1.0 op_sel_hi:[1,0]
	v_pk_add_f32 v[178:179], v[178:179], 1.0 op_sel_hi:[1,0]
	v_rcp_f32_e32 v172, v172
	v_rcp_f32_e32 v173, v173
	v_rcp_f32_e32 v174, v174
	v_rcp_f32_e32 v175, v175
	v_rcp_f32_e32 v176, v176
	v_rcp_f32_e32 v177, v177
	v_rcp_f32_e32 v178, v178
	v_rcp_f32_e32 v179, v179
	v_pk_mul_f32 v[94:95], v[94:95], v[172:173]
	v_pk_mul_f32 v[96:97], v[96:97], v[174:175]
	v_pk_mul_f32 v[90:91], v[90:91], v[176:177]
	v_pk_mul_f32 v[92:93], v[92:93], v[178:179]
	v_cvt_pk_bf16_f32 v168, v94, v95
	v_cvt_pk_bf16_f32 v169, v96, v97
	v_cvt_pk_bf16_f32 v170, v90, v91
	v_cvt_pk_bf16_f32 v171, v92, v93
	global_store_dwordx4 v189, v[168:171], s[80:81]
	v_pk_fma_f32 v[86:87], v[86:87], v[192:193], v[58:59] op_sel_hi:[1,0,1]
	v_pk_fma_f32 v[88:89], v[88:89], v[192:193], v[60:61] op_sel_hi:[1,0,1]
	v_pk_fma_f32 v[82:83], v[82:83], v[192:193], v[62:63] op_sel_hi:[1,0,1]
	v_pk_fma_f32 v[84:85], v[84:85], v[192:193], v[64:65] op_sel_hi:[1,0,1]
	v_pk_mul_f32 v[172:173], v[86:87], s[84:85] op_sel_hi:[1,0]
	v_pk_mul_f32 v[174:175], v[88:89], s[84:85] op_sel_hi:[1,0]
	v_pk_mul_f32 v[176:177], v[82:83], s[84:85] op_sel_hi:[1,0]
	v_pk_mul_f32 v[178:179], v[84:85], s[84:85] op_sel_hi:[1,0]
	v_pk_mul_f32 v[172:173], v[86:87], v[172:173]
	v_pk_mul_f32 v[174:175], v[88:89], v[174:175]
	v_pk_mul_f32 v[176:177], v[82:83], v[176:177]
	v_pk_mul_f32 v[178:179], v[84:85], v[178:179]
	v_pk_fma_f32 v[172:173], v[86:87], v[172:173], v[86:87]
	v_pk_fma_f32 v[174:175], v[88:89], v[174:175], v[88:89]
	v_pk_fma_f32 v[176:177], v[82:83], v[176:177], v[82:83]
	v_pk_fma_f32 v[178:179], v[84:85], v[178:179], v[84:85]
	v_pk_mul_f32 v[172:173], v[172:173], s[86:87] op_sel_hi:[1,0]
	v_pk_mul_f32 v[174:175], v[174:175], s[86:87] op_sel_hi:[1,0]
	v_pk_mul_f32 v[176:177], v[176:177], s[86:87] op_sel_hi:[1,0]
	v_pk_mul_f32 v[178:179], v[178:179], s[86:87] op_sel_hi:[1,0]
	v_pk_mul_f32 v[172:173], v[172:173], s[88:89] op_sel_hi:[1,0]
	v_pk_mul_f32 v[174:175], v[174:175], s[88:89] op_sel_hi:[1,0]
	v_pk_mul_f32 v[176:177], v[176:177], s[88:89] op_sel_hi:[1,0]
	v_pk_mul_f32 v[178:179], v[178:179], s[88:89] op_sel_hi:[1,0]
	v_exp_f32_e32 v172, v172
	v_exp_f32_e32 v173, v173
	v_exp_f32_e32 v174, v174
	v_exp_f32_e32 v175, v175
	v_exp_f32_e32 v176, v176
	v_exp_f32_e32 v177, v177
	v_exp_f32_e32 v178, v178
	v_exp_f32_e32 v179, v179
	v_pk_add_f32 v[172:173], v[172:173], 1.0 op_sel_hi:[1,0]
	v_pk_add_f32 v[174:175], v[174:175], 1.0 op_sel_hi:[1,0]
	v_pk_add_f32 v[176:177], v[176:177], 1.0 op_sel_hi:[1,0]
	v_pk_add_f32 v[178:179], v[178:179], 1.0 op_sel_hi:[1,0]
	v_rcp_f32_e32 v172, v172
	v_rcp_f32_e32 v173, v173
	v_rcp_f32_e32 v174, v174
	v_rcp_f32_e32 v175, v175
	v_rcp_f32_e32 v176, v176
	v_rcp_f32_e32 v177, v177
	v_rcp_f32_e32 v178, v178
	v_rcp_f32_e32 v179, v179
	v_pk_mul_f32 v[86:87], v[86:87], v[172:173]
	v_pk_mul_f32 v[88:89], v[88:89], v[174:175]
	v_pk_mul_f32 v[82:83], v[82:83], v[176:177]
	v_pk_mul_f32 v[84:85], v[84:85], v[178:179]
	s_nop 0
	v_cvt_pk_bf16_f32 v168, v86, v87
	v_cvt_pk_bf16_f32 v169, v88, v89
	v_cvt_pk_bf16_f32 v170, v82, v83
	v_cvt_pk_bf16_f32 v171, v84, v85
	global_store_dwordx4 v189, v[168:171], s[80:81] offset:256
	s_add_u32 s80, s10, 0x100000
	s_addc_u32 s81, s11, 0
	v_pk_fma_f32 v[78:79], v[78:79], v[194:195], v[42:43] op_sel_hi:[1,0,1]
	v_pk_fma_f32 v[80:81], v[80:81], v[194:195], v[44:45] op_sel_hi:[1,0,1]
	v_pk_fma_f32 v[74:75], v[74:75], v[194:195], v[46:47] op_sel_hi:[1,0,1]
	v_pk_fma_f32 v[76:77], v[76:77], v[194:195], v[48:49] op_sel_hi:[1,0,1]
	v_pk_mul_f32 v[172:173], v[78:79], s[84:85] op_sel_hi:[1,0]
	v_pk_mul_f32 v[174:175], v[80:81], s[84:85] op_sel_hi:[1,0]
	v_pk_mul_f32 v[176:177], v[74:75], s[84:85] op_sel_hi:[1,0]
	v_pk_mul_f32 v[178:179], v[76:77], s[84:85] op_sel_hi:[1,0]
	v_pk_mul_f32 v[172:173], v[78:79], v[172:173]
	v_pk_mul_f32 v[174:175], v[80:81], v[174:175]
	v_pk_mul_f32 v[176:177], v[74:75], v[176:177]
	v_pk_mul_f32 v[178:179], v[76:77], v[178:179]
	v_pk_fma_f32 v[172:173], v[78:79], v[172:173], v[78:79]
	v_pk_fma_f32 v[174:175], v[80:81], v[174:175], v[80:81]
	v_pk_fma_f32 v[176:177], v[74:75], v[176:177], v[74:75]
	v_pk_fma_f32 v[178:179], v[76:77], v[178:179], v[76:77]
	v_pk_mul_f32 v[172:173], v[172:173], s[86:87] op_sel_hi:[1,0]
	v_pk_mul_f32 v[174:175], v[174:175], s[86:87] op_sel_hi:[1,0]
	v_pk_mul_f32 v[176:177], v[176:177], s[86:87] op_sel_hi:[1,0]
	v_pk_mul_f32 v[178:179], v[178:179], s[86:87] op_sel_hi:[1,0]
	v_pk_mul_f32 v[172:173], v[172:173], s[88:89] op_sel_hi:[1,0]
	v_pk_mul_f32 v[174:175], v[174:175], s[88:89] op_sel_hi:[1,0]
	v_pk_mul_f32 v[176:177], v[176:177], s[88:89] op_sel_hi:[1,0]
	v_pk_mul_f32 v[178:179], v[178:179], s[88:89] op_sel_hi:[1,0]
	v_exp_f32_e32 v172, v172
	v_exp_f32_e32 v173, v173
	v_exp_f32_e32 v174, v174
	v_exp_f32_e32 v175, v175
	v_exp_f32_e32 v176, v176
	v_exp_f32_e32 v177, v177
	v_exp_f32_e32 v178, v178
	v_exp_f32_e32 v179, v179
	v_pk_add_f32 v[172:173], v[172:173], 1.0 op_sel_hi:[1,0]
	v_pk_add_f32 v[174:175], v[174:175], 1.0 op_sel_hi:[1,0]
	v_pk_add_f32 v[176:177], v[176:177], 1.0 op_sel_hi:[1,0]
	v_pk_add_f32 v[178:179], v[178:179], 1.0 op_sel_hi:[1,0]
	v_rcp_f32_e32 v172, v172
	v_rcp_f32_e32 v173, v173
	v_rcp_f32_e32 v174, v174
	v_rcp_f32_e32 v175, v175
	v_rcp_f32_e32 v176, v176
	v_rcp_f32_e32 v177, v177
	v_rcp_f32_e32 v178, v178
	v_rcp_f32_e32 v179, v179
	v_pk_mul_f32 v[78:79], v[78:79], v[172:173]
	v_pk_mul_f32 v[80:81], v[80:81], v[174:175]
	v_pk_mul_f32 v[74:75], v[74:75], v[176:177]
	v_pk_mul_f32 v[76:77], v[76:77], v[178:179]
	v_cvt_pk_bf16_f32 v168, v78, v79
	v_cvt_pk_bf16_f32 v169, v80, v81
	v_cvt_pk_bf16_f32 v170, v74, v75
	v_cvt_pk_bf16_f32 v171, v76, v77
	global_store_dwordx4 v189, v[168:171], s[80:81]
	v_pk_fma_f32 v[70:71], v[70:71], v[194:195], v[58:59] op_sel_hi:[1,0,1]
	v_pk_fma_f32 v[72:73], v[72:73], v[194:195], v[60:61] op_sel_hi:[1,0,1]
	v_pk_fma_f32 v[66:67], v[66:67], v[194:195], v[62:63] op_sel_hi:[1,0,1]
	v_pk_fma_f32 v[68:69], v[68:69], v[194:195], v[64:65] op_sel_hi:[1,0,1]
	v_pk_mul_f32 v[172:173], v[70:71], s[84:85] op_sel_hi:[1,0]
	v_pk_mul_f32 v[174:175], v[72:73], s[84:85] op_sel_hi:[1,0]
	v_pk_mul_f32 v[176:177], v[66:67], s[84:85] op_sel_hi:[1,0]
	v_pk_mul_f32 v[178:179], v[68:69], s[84:85] op_sel_hi:[1,0]
	v_pk_mul_f32 v[172:173], v[70:71], v[172:173]
	v_pk_mul_f32 v[174:175], v[72:73], v[174:175]
	v_pk_mul_f32 v[176:177], v[66:67], v[176:177]
	v_pk_mul_f32 v[178:179], v[68:69], v[178:179]
	v_pk_fma_f32 v[172:173], v[70:71], v[172:173], v[70:71]
	v_pk_fma_f32 v[174:175], v[72:73], v[174:175], v[72:73]
	v_pk_fma_f32 v[176:177], v[66:67], v[176:177], v[66:67]
	v_pk_fma_f32 v[178:179], v[68:69], v[178:179], v[68:69]
	v_pk_mul_f32 v[172:173], v[172:173], s[86:87] op_sel_hi:[1,0]
	v_pk_mul_f32 v[174:175], v[174:175], s[86:87] op_sel_hi:[1,0]
	v_pk_mul_f32 v[176:177], v[176:177], s[86:87] op_sel_hi:[1,0]
	v_pk_mul_f32 v[178:179], v[178:179], s[86:87] op_sel_hi:[1,0]
	v_pk_mul_f32 v[172:173], v[172:173], s[88:89] op_sel_hi:[1,0]
	v_pk_mul_f32 v[174:175], v[174:175], s[88:89] op_sel_hi:[1,0]
	v_pk_mul_f32 v[176:177], v[176:177], s[88:89] op_sel_hi:[1,0]
	v_pk_mul_f32 v[178:179], v[178:179], s[88:89] op_sel_hi:[1,0]
	v_exp_f32_e32 v172, v172
	v_exp_f32_e32 v173, v173
	v_exp_f32_e32 v174, v174
	v_exp_f32_e32 v175, v175
	v_exp_f32_e32 v176, v176
	v_exp_f32_e32 v177, v177
	v_exp_f32_e32 v178, v178
	v_exp_f32_e32 v179, v179
	v_pk_add_f32 v[172:173], v[172:173], 1.0 op_sel_hi:[1,0]
	v_pk_add_f32 v[174:175], v[174:175], 1.0 op_sel_hi:[1,0]
	v_pk_add_f32 v[176:177], v[176:177], 1.0 op_sel_hi:[1,0]
	v_pk_add_f32 v[178:179], v[178:179], 1.0 op_sel_hi:[1,0]
	v_rcp_f32_e32 v172, v172
	v_rcp_f32_e32 v173, v173
	v_rcp_f32_e32 v174, v174
	v_rcp_f32_e32 v175, v175
	v_rcp_f32_e32 v176, v176
	v_rcp_f32_e32 v177, v177
	v_rcp_f32_e32 v178, v178
	v_rcp_f32_e32 v179, v179
	v_pk_mul_f32 v[70:71], v[70:71], v[172:173]
	v_pk_mul_f32 v[72:73], v[72:73], v[174:175]
	v_pk_mul_f32 v[66:67], v[66:67], v[176:177]
	v_pk_mul_f32 v[68:69], v[68:69], v[178:179]
	s_nop 0
	v_cvt_pk_bf16_f32 v168, v70, v71
	v_cvt_pk_bf16_f32 v169, v72, v73
	v_cvt_pk_bf16_f32 v170, v66, v67
	v_cvt_pk_bf16_f32 v171, v68, v69
	global_store_dwordx4 v189, v[168:171], s[80:81] offset:256
	s_add_u32 s80, s10, 0x120000
	s_addc_u32 s81, s11, 0
	v_pk_fma_f32 v[54:55], v[54:55], v[196:197], v[42:43] op_sel_hi:[1,0,1]
	v_pk_fma_f32 v[56:57], v[56:57], v[196:197], v[44:45] op_sel_hi:[1,0,1]
	v_pk_fma_f32 v[50:51], v[50:51], v[196:197], v[46:47] op_sel_hi:[1,0,1]
	v_pk_fma_f32 v[52:53], v[52:53], v[196:197], v[48:49] op_sel_hi:[1,0,1]
	v_pk_mul_f32 v[172:173], v[54:55], s[84:85] op_sel_hi:[1,0]
	v_pk_mul_f32 v[174:175], v[56:57], s[84:85] op_sel_hi:[1,0]
	v_pk_mul_f32 v[176:177], v[50:51], s[84:85] op_sel_hi:[1,0]
	v_pk_mul_f32 v[178:179], v[52:53], s[84:85] op_sel_hi:[1,0]
	v_pk_mul_f32 v[172:173], v[54:55], v[172:173]
	v_pk_mul_f32 v[174:175], v[56:57], v[174:175]
	v_pk_mul_f32 v[176:177], v[50:51], v[176:177]
	v_pk_mul_f32 v[178:179], v[52:53], v[178:179]
	v_pk_fma_f32 v[172:173], v[54:55], v[172:173], v[54:55]
	v_pk_fma_f32 v[174:175], v[56:57], v[174:175], v[56:57]
	v_pk_fma_f32 v[176:177], v[50:51], v[176:177], v[50:51]
	v_pk_fma_f32 v[178:179], v[52:53], v[178:179], v[52:53]
	v_pk_mul_f32 v[172:173], v[172:173], s[86:87] op_sel_hi:[1,0]
	v_pk_mul_f32 v[174:175], v[174:175], s[86:87] op_sel_hi:[1,0]
	v_pk_mul_f32 v[176:177], v[176:177], s[86:87] op_sel_hi:[1,0]
	v_pk_mul_f32 v[178:179], v[178:179], s[86:87] op_sel_hi:[1,0]
	v_pk_mul_f32 v[172:173], v[172:173], s[88:89] op_sel_hi:[1,0]
	v_pk_mul_f32 v[174:175], v[174:175], s[88:89] op_sel_hi:[1,0]
	v_pk_mul_f32 v[176:177], v[176:177], s[88:89] op_sel_hi:[1,0]
	v_pk_mul_f32 v[178:179], v[178:179], s[88:89] op_sel_hi:[1,0]
	v_exp_f32_e32 v172, v172
	v_exp_f32_e32 v173, v173
	v_exp_f32_e32 v174, v174
	v_exp_f32_e32 v175, v175
	v_exp_f32_e32 v176, v176
	v_exp_f32_e32 v177, v177
	v_exp_f32_e32 v178, v178
	v_exp_f32_e32 v179, v179
	v_pk_add_f32 v[172:173], v[172:173], 1.0 op_sel_hi:[1,0]
	v_pk_add_f32 v[174:175], v[174:175], 1.0 op_sel_hi:[1,0]
	v_pk_add_f32 v[176:177], v[176:177], 1.0 op_sel_hi:[1,0]
	v_pk_add_f32 v[178:179], v[178:179], 1.0 op_sel_hi:[1,0]
	v_rcp_f32_e32 v172, v172
	v_rcp_f32_e32 v173, v173
	v_rcp_f32_e32 v174, v174
	v_rcp_f32_e32 v175, v175
	v_rcp_f32_e32 v176, v176
	v_rcp_f32_e32 v177, v177
	v_rcp_f32_e32 v178, v178
	v_rcp_f32_e32 v179, v179
	v_pk_mul_f32 v[54:55], v[54:55], v[172:173]
	v_pk_mul_f32 v[56:57], v[56:57], v[174:175]
	v_pk_mul_f32 v[50:51], v[50:51], v[176:177]
	v_pk_mul_f32 v[52:53], v[52:53], v[178:179]
	v_cvt_pk_bf16_f32 v168, v54, v55
	v_cvt_pk_bf16_f32 v169, v56, v57
	v_cvt_pk_bf16_f32 v170, v50, v51
	v_cvt_pk_bf16_f32 v171, v52, v53
	global_store_dwordx4 v189, v[168:171], s[80:81]
	v_pk_fma_f32 v[38:39], v[38:39], v[196:197], v[58:59] op_sel_hi:[1,0,1]
	v_pk_fma_f32 v[40:41], v[40:41], v[196:197], v[60:61] op_sel_hi:[1,0,1]
	v_pk_fma_f32 v[34:35], v[34:35], v[196:197], v[62:63] op_sel_hi:[1,0,1]
	v_pk_fma_f32 v[36:37], v[36:37], v[196:197], v[64:65] op_sel_hi:[1,0,1]
	v_pk_mul_f32 v[172:173], v[38:39], s[84:85] op_sel_hi:[1,0]
	v_pk_mul_f32 v[174:175], v[40:41], s[84:85] op_sel_hi:[1,0]
	v_pk_mul_f32 v[176:177], v[34:35], s[84:85] op_sel_hi:[1,0]
	v_pk_mul_f32 v[178:179], v[36:37], s[84:85] op_sel_hi:[1,0]
	v_pk_mul_f32 v[172:173], v[38:39], v[172:173]
	v_pk_mul_f32 v[174:175], v[40:41], v[174:175]
	v_pk_mul_f32 v[176:177], v[34:35], v[176:177]
	v_pk_mul_f32 v[178:179], v[36:37], v[178:179]
	v_pk_fma_f32 v[172:173], v[38:39], v[172:173], v[38:39]
	v_pk_fma_f32 v[174:175], v[40:41], v[174:175], v[40:41]
	v_pk_fma_f32 v[176:177], v[34:35], v[176:177], v[34:35]
	v_pk_fma_f32 v[178:179], v[36:37], v[178:179], v[36:37]
	v_pk_mul_f32 v[172:173], v[172:173], s[86:87] op_sel_hi:[1,0]
	v_pk_mul_f32 v[174:175], v[174:175], s[86:87] op_sel_hi:[1,0]
	v_pk_mul_f32 v[176:177], v[176:177], s[86:87] op_sel_hi:[1,0]
	v_pk_mul_f32 v[178:179], v[178:179], s[86:87] op_sel_hi:[1,0]
	v_pk_mul_f32 v[172:173], v[172:173], s[88:89] op_sel_hi:[1,0]
	v_pk_mul_f32 v[174:175], v[174:175], s[88:89] op_sel_hi:[1,0]
	v_pk_mul_f32 v[176:177], v[176:177], s[88:89] op_sel_hi:[1,0]
	v_pk_mul_f32 v[178:179], v[178:179], s[88:89] op_sel_hi:[1,0]
	v_exp_f32_e32 v172, v172
	v_exp_f32_e32 v173, v173
	v_exp_f32_e32 v174, v174
	v_exp_f32_e32 v175, v175
	v_exp_f32_e32 v176, v176
	v_exp_f32_e32 v177, v177
	v_exp_f32_e32 v178, v178
	v_exp_f32_e32 v179, v179
	v_pk_add_f32 v[172:173], v[172:173], 1.0 op_sel_hi:[1,0]
	v_pk_add_f32 v[174:175], v[174:175], 1.0 op_sel_hi:[1,0]
	v_pk_add_f32 v[176:177], v[176:177], 1.0 op_sel_hi:[1,0]
	v_pk_add_f32 v[178:179], v[178:179], 1.0 op_sel_hi:[1,0]
	v_rcp_f32_e32 v172, v172
	v_rcp_f32_e32 v173, v173
	v_rcp_f32_e32 v174, v174
	v_rcp_f32_e32 v175, v175
	v_rcp_f32_e32 v176, v176
	v_rcp_f32_e32 v177, v177
	v_rcp_f32_e32 v178, v178
	v_rcp_f32_e32 v179, v179
	v_pk_mul_f32 v[38:39], v[38:39], v[172:173]
	v_pk_mul_f32 v[40:41], v[40:41], v[174:175]
	v_pk_mul_f32 v[34:35], v[34:35], v[176:177]
	v_pk_mul_f32 v[36:37], v[36:37], v[178:179]
	s_nop 0
	v_cvt_pk_bf16_f32 v168, v38, v39
	v_cvt_pk_bf16_f32 v169, v40, v41
	v_cvt_pk_bf16_f32 v170, v34, v35
	v_cvt_pk_bf16_f32 v171, v36, v37
	global_store_dwordx4 v189, v[168:171], s[80:81] offset:256
	s_add_u32 s80, s10, 0x140000
	s_addc_u32 s81, s11, 0
	v_pk_fma_f32 v[30:31], v[30:31], v[210:211], v[42:43] op_sel_hi:[1,0,1]
	v_pk_fma_f32 v[32:33], v[32:33], v[210:211], v[44:45] op_sel_hi:[1,0,1]
	v_pk_fma_f32 v[26:27], v[26:27], v[210:211], v[46:47] op_sel_hi:[1,0,1]
	v_pk_fma_f32 v[28:29], v[28:29], v[210:211], v[48:49] op_sel_hi:[1,0,1]
	v_pk_mul_f32 v[172:173], v[30:31], s[84:85] op_sel_hi:[1,0]
	v_pk_mul_f32 v[174:175], v[32:33], s[84:85] op_sel_hi:[1,0]
	v_pk_mul_f32 v[176:177], v[26:27], s[84:85] op_sel_hi:[1,0]
	v_pk_mul_f32 v[178:179], v[28:29], s[84:85] op_sel_hi:[1,0]
	v_pk_mul_f32 v[172:173], v[30:31], v[172:173]
	v_pk_mul_f32 v[174:175], v[32:33], v[174:175]
	v_pk_mul_f32 v[176:177], v[26:27], v[176:177]
	v_pk_mul_f32 v[178:179], v[28:29], v[178:179]
	v_pk_fma_f32 v[172:173], v[30:31], v[172:173], v[30:31]
	v_pk_fma_f32 v[174:175], v[32:33], v[174:175], v[32:33]
	v_pk_fma_f32 v[176:177], v[26:27], v[176:177], v[26:27]
	v_pk_fma_f32 v[178:179], v[28:29], v[178:179], v[28:29]
	v_pk_mul_f32 v[172:173], v[172:173], s[86:87] op_sel_hi:[1,0]
	v_pk_mul_f32 v[174:175], v[174:175], s[86:87] op_sel_hi:[1,0]
	v_pk_mul_f32 v[176:177], v[176:177], s[86:87] op_sel_hi:[1,0]
	v_pk_mul_f32 v[178:179], v[178:179], s[86:87] op_sel_hi:[1,0]
	v_pk_mul_f32 v[172:173], v[172:173], s[88:89] op_sel_hi:[1,0]
	v_pk_mul_f32 v[174:175], v[174:175], s[88:89] op_sel_hi:[1,0]
	v_pk_mul_f32 v[176:177], v[176:177], s[88:89] op_sel_hi:[1,0]
	v_pk_mul_f32 v[178:179], v[178:179], s[88:89] op_sel_hi:[1,0]
	v_exp_f32_e32 v172, v172
	v_exp_f32_e32 v173, v173
	v_exp_f32_e32 v174, v174
	v_exp_f32_e32 v175, v175
	v_exp_f32_e32 v176, v176
	v_exp_f32_e32 v177, v177
	v_exp_f32_e32 v178, v178
	v_exp_f32_e32 v179, v179
	v_pk_add_f32 v[172:173], v[172:173], 1.0 op_sel_hi:[1,0]
	v_pk_add_f32 v[174:175], v[174:175], 1.0 op_sel_hi:[1,0]
	v_pk_add_f32 v[176:177], v[176:177], 1.0 op_sel_hi:[1,0]
	v_pk_add_f32 v[178:179], v[178:179], 1.0 op_sel_hi:[1,0]
	v_rcp_f32_e32 v172, v172
	v_rcp_f32_e32 v173, v173
	v_rcp_f32_e32 v174, v174
	v_rcp_f32_e32 v175, v175
	v_rcp_f32_e32 v176, v176
	v_rcp_f32_e32 v177, v177
	v_rcp_f32_e32 v178, v178
	v_rcp_f32_e32 v179, v179
	v_pk_mul_f32 v[30:31], v[30:31], v[172:173]
	v_pk_mul_f32 v[32:33], v[32:33], v[174:175]
	v_pk_mul_f32 v[26:27], v[26:27], v[176:177]
	v_pk_mul_f32 v[28:29], v[28:29], v[178:179]
	v_cvt_pk_bf16_f32 v168, v30, v31
	v_cvt_pk_bf16_f32 v169, v32, v33
	v_cvt_pk_bf16_f32 v170, v26, v27
	v_cvt_pk_bf16_f32 v171, v28, v29
	global_store_dwordx4 v189, v[168:171], s[80:81]
	v_pk_fma_f32 v[22:23], v[22:23], v[210:211], v[58:59] op_sel_hi:[1,0,1]
	v_pk_fma_f32 v[24:25], v[24:25], v[210:211], v[60:61] op_sel_hi:[1,0,1]
	v_pk_fma_f32 v[18:19], v[18:19], v[210:211], v[62:63] op_sel_hi:[1,0,1]
	v_pk_fma_f32 v[20:21], v[20:21], v[210:211], v[64:65] op_sel_hi:[1,0,1]
	v_pk_mul_f32 v[172:173], v[22:23], s[84:85] op_sel_hi:[1,0]
	v_pk_mul_f32 v[174:175], v[24:25], s[84:85] op_sel_hi:[1,0]
	v_pk_mul_f32 v[176:177], v[18:19], s[84:85] op_sel_hi:[1,0]
	v_pk_mul_f32 v[178:179], v[20:21], s[84:85] op_sel_hi:[1,0]
	v_pk_mul_f32 v[172:173], v[22:23], v[172:173]
	v_pk_mul_f32 v[174:175], v[24:25], v[174:175]
	v_pk_mul_f32 v[176:177], v[18:19], v[176:177]
	v_pk_mul_f32 v[178:179], v[20:21], v[178:179]
	v_pk_fma_f32 v[172:173], v[22:23], v[172:173], v[22:23]
	v_pk_fma_f32 v[174:175], v[24:25], v[174:175], v[24:25]
	v_pk_fma_f32 v[176:177], v[18:19], v[176:177], v[18:19]
	v_pk_fma_f32 v[178:179], v[20:21], v[178:179], v[20:21]
	v_pk_mul_f32 v[172:173], v[172:173], s[86:87] op_sel_hi:[1,0]
	v_pk_mul_f32 v[174:175], v[174:175], s[86:87] op_sel_hi:[1,0]
	v_pk_mul_f32 v[176:177], v[176:177], s[86:87] op_sel_hi:[1,0]
	v_pk_mul_f32 v[178:179], v[178:179], s[86:87] op_sel_hi:[1,0]
	v_pk_mul_f32 v[172:173], v[172:173], s[88:89] op_sel_hi:[1,0]
	v_pk_mul_f32 v[174:175], v[174:175], s[88:89] op_sel_hi:[1,0]
	v_pk_mul_f32 v[176:177], v[176:177], s[88:89] op_sel_hi:[1,0]
	v_pk_mul_f32 v[178:179], v[178:179], s[88:89] op_sel_hi:[1,0]
	v_exp_f32_e32 v172, v172
	v_exp_f32_e32 v173, v173
	v_exp_f32_e32 v174, v174
	v_exp_f32_e32 v175, v175
	v_exp_f32_e32 v176, v176
	v_exp_f32_e32 v177, v177
	v_exp_f32_e32 v178, v178
	v_exp_f32_e32 v179, v179
	v_pk_add_f32 v[172:173], v[172:173], 1.0 op_sel_hi:[1,0]
	v_pk_add_f32 v[174:175], v[174:175], 1.0 op_sel_hi:[1,0]
	v_pk_add_f32 v[176:177], v[176:177], 1.0 op_sel_hi:[1,0]
	v_pk_add_f32 v[178:179], v[178:179], 1.0 op_sel_hi:[1,0]
	v_rcp_f32_e32 v172, v172
	v_rcp_f32_e32 v173, v173
	v_rcp_f32_e32 v174, v174
	v_rcp_f32_e32 v175, v175
	v_rcp_f32_e32 v176, v176
	v_rcp_f32_e32 v177, v177
	v_rcp_f32_e32 v178, v178
	v_rcp_f32_e32 v179, v179
	v_pk_mul_f32 v[22:23], v[22:23], v[172:173]
	v_pk_mul_f32 v[24:25], v[24:25], v[174:175]
	v_pk_mul_f32 v[18:19], v[18:19], v[176:177]
	v_pk_mul_f32 v[20:21], v[20:21], v[178:179]
	s_nop 0
	v_cvt_pk_bf16_f32 v168, v22, v23
	v_cvt_pk_bf16_f32 v169, v24, v25
	v_cvt_pk_bf16_f32 v170, v18, v19
	v_cvt_pk_bf16_f32 v171, v20, v21
	global_store_dwordx4 v189, v[168:171], s[80:81] offset:256
	s_add_u32 s80, s10, 0x160000
	s_addc_u32 s81, s11, 0
	v_pk_fma_f32 v[14:15], v[14:15], v[212:213], v[42:43] op_sel_hi:[1,0,1]
	v_pk_fma_f32 v[16:17], v[16:17], v[212:213], v[44:45] op_sel_hi:[1,0,1]
	v_pk_fma_f32 v[10:11], v[10:11], v[212:213], v[46:47] op_sel_hi:[1,0,1]
	v_pk_fma_f32 v[12:13], v[12:13], v[212:213], v[48:49] op_sel_hi:[1,0,1]
	v_pk_mul_f32 v[172:173], v[14:15], s[84:85] op_sel_hi:[1,0]
	v_pk_mul_f32 v[174:175], v[16:17], s[84:85] op_sel_hi:[1,0]
	v_pk_mul_f32 v[176:177], v[10:11], s[84:85] op_sel_hi:[1,0]
	v_pk_mul_f32 v[178:179], v[12:13], s[84:85] op_sel_hi:[1,0]
	v_pk_mul_f32 v[172:173], v[14:15], v[172:173]
	v_pk_mul_f32 v[174:175], v[16:17], v[174:175]
	v_pk_mul_f32 v[176:177], v[10:11], v[176:177]
	v_pk_mul_f32 v[178:179], v[12:13], v[178:179]
	v_pk_fma_f32 v[172:173], v[14:15], v[172:173], v[14:15]
	v_pk_fma_f32 v[174:175], v[16:17], v[174:175], v[16:17]
	v_pk_fma_f32 v[176:177], v[10:11], v[176:177], v[10:11]
	v_pk_fma_f32 v[178:179], v[12:13], v[178:179], v[12:13]
	v_pk_mul_f32 v[172:173], v[172:173], s[86:87] op_sel_hi:[1,0]
	v_pk_mul_f32 v[174:175], v[174:175], s[86:87] op_sel_hi:[1,0]
	v_pk_mul_f32 v[176:177], v[176:177], s[86:87] op_sel_hi:[1,0]
	v_pk_mul_f32 v[178:179], v[178:179], s[86:87] op_sel_hi:[1,0]
	v_pk_mul_f32 v[172:173], v[172:173], s[88:89] op_sel_hi:[1,0]
	v_pk_mul_f32 v[174:175], v[174:175], s[88:89] op_sel_hi:[1,0]
	v_pk_mul_f32 v[176:177], v[176:177], s[88:89] op_sel_hi:[1,0]
	v_pk_mul_f32 v[178:179], v[178:179], s[88:89] op_sel_hi:[1,0]
	v_exp_f32_e32 v172, v172
	v_exp_f32_e32 v173, v173
	v_exp_f32_e32 v174, v174
	v_exp_f32_e32 v175, v175
	v_exp_f32_e32 v176, v176
	v_exp_f32_e32 v177, v177
	v_exp_f32_e32 v178, v178
	v_exp_f32_e32 v179, v179
	v_pk_add_f32 v[172:173], v[172:173], 1.0 op_sel_hi:[1,0]
	v_pk_add_f32 v[174:175], v[174:175], 1.0 op_sel_hi:[1,0]
	v_pk_add_f32 v[176:177], v[176:177], 1.0 op_sel_hi:[1,0]
	v_pk_add_f32 v[178:179], v[178:179], 1.0 op_sel_hi:[1,0]
	v_rcp_f32_e32 v172, v172
	v_rcp_f32_e32 v173, v173
	v_rcp_f32_e32 v174, v174
	v_rcp_f32_e32 v175, v175
	v_rcp_f32_e32 v176, v176
	v_rcp_f32_e32 v177, v177
	v_rcp_f32_e32 v178, v178
	v_rcp_f32_e32 v179, v179
	v_pk_mul_f32 v[14:15], v[14:15], v[172:173]
	v_pk_mul_f32 v[16:17], v[16:17], v[174:175]
	v_pk_mul_f32 v[10:11], v[10:11], v[176:177]
	v_pk_mul_f32 v[12:13], v[12:13], v[178:179]
	v_cvt_pk_bf16_f32 v168, v14, v15
	v_cvt_pk_bf16_f32 v169, v16, v17
	v_cvt_pk_bf16_f32 v170, v10, v11
	v_cvt_pk_bf16_f32 v171, v12, v13
	global_store_dwordx4 v189, v[168:171], s[80:81]
	v_pk_fma_f32 v[6:7], v[6:7], v[212:213], v[58:59] op_sel_hi:[1,0,1]
	v_pk_fma_f32 v[8:9], v[8:9], v[212:213], v[60:61] op_sel_hi:[1,0,1]
	v_pk_fma_f32 v[2:3], v[2:3], v[212:213], v[62:63] op_sel_hi:[1,0,1]
	v_pk_fma_f32 v[4:5], v[4:5], v[212:213], v[64:65] op_sel_hi:[1,0,1]
	v_pk_mul_f32 v[172:173], v[6:7], s[84:85] op_sel_hi:[1,0]
	v_pk_mul_f32 v[174:175], v[8:9], s[84:85] op_sel_hi:[1,0]
	v_pk_mul_f32 v[176:177], v[2:3], s[84:85] op_sel_hi:[1,0]
	v_pk_mul_f32 v[178:179], v[4:5], s[84:85] op_sel_hi:[1,0]
	v_pk_mul_f32 v[172:173], v[6:7], v[172:173]
	v_pk_mul_f32 v[174:175], v[8:9], v[174:175]
	v_pk_mul_f32 v[176:177], v[2:3], v[176:177]
	v_pk_mul_f32 v[178:179], v[4:5], v[178:179]
	v_pk_fma_f32 v[172:173], v[6:7], v[172:173], v[6:7]
	v_pk_fma_f32 v[174:175], v[8:9], v[174:175], v[8:9]
	v_pk_fma_f32 v[176:177], v[2:3], v[176:177], v[2:3]
	v_pk_fma_f32 v[178:179], v[4:5], v[178:179], v[4:5]
	v_pk_mul_f32 v[172:173], v[172:173], s[86:87] op_sel_hi:[1,0]
	v_pk_mul_f32 v[174:175], v[174:175], s[86:87] op_sel_hi:[1,0]
	v_pk_mul_f32 v[176:177], v[176:177], s[86:87] op_sel_hi:[1,0]
	v_pk_mul_f32 v[178:179], v[178:179], s[86:87] op_sel_hi:[1,0]
	v_pk_mul_f32 v[172:173], v[172:173], s[88:89] op_sel_hi:[1,0]
	v_pk_mul_f32 v[174:175], v[174:175], s[88:89] op_sel_hi:[1,0]
	v_pk_mul_f32 v[176:177], v[176:177], s[88:89] op_sel_hi:[1,0]
	v_pk_mul_f32 v[178:179], v[178:179], s[88:89] op_sel_hi:[1,0]
	v_exp_f32_e32 v172, v172
	v_exp_f32_e32 v173, v173
	v_exp_f32_e32 v174, v174
	v_exp_f32_e32 v175, v175
	v_exp_f32_e32 v176, v176
	v_exp_f32_e32 v177, v177
	v_exp_f32_e32 v178, v178
	v_exp_f32_e32 v179, v179
	v_pk_add_f32 v[172:173], v[172:173], 1.0 op_sel_hi:[1,0]
	v_pk_add_f32 v[174:175], v[174:175], 1.0 op_sel_hi:[1,0]
	v_pk_add_f32 v[176:177], v[176:177], 1.0 op_sel_hi:[1,0]
	v_pk_add_f32 v[178:179], v[178:179], 1.0 op_sel_hi:[1,0]
	v_rcp_f32_e32 v172, v172
	v_rcp_f32_e32 v173, v173
	v_rcp_f32_e32 v174, v174
	v_rcp_f32_e32 v175, v175
	v_rcp_f32_e32 v176, v176
	v_rcp_f32_e32 v177, v177
	v_rcp_f32_e32 v178, v178
	v_rcp_f32_e32 v179, v179
	v_pk_mul_f32 v[6:7], v[6:7], v[172:173]
	v_pk_mul_f32 v[8:9], v[8:9], v[174:175]
	v_pk_mul_f32 v[2:3], v[2:3], v[176:177]
	v_pk_mul_f32 v[4:5], v[4:5], v[178:179]
	s_nop 0
	v_cvt_pk_bf16_f32 v168, v6, v7
	v_cvt_pk_bf16_f32 v169, v8, v9
	v_cvt_pk_bf16_f32 v170, v2, v3
	v_cvt_pk_bf16_f32 v171, v4, v5
	global_store_dwordx4 v189, v[168:171], s[80:81] offset:256
	s_branch .Lact0_rgin_done
.Lact0_rgin_id:
	s_waitcnt lgkmcnt(0)
	s_add_u32 s80, s10, 0x0
	s_addc_u32 s81, s11, 0
	v_pk_fma_f32 v[142:143], v[142:143], v[180:181], v[42:43] op_sel_hi:[1,0,1]
	v_pk_fma_f32 v[144:145], v[144:145], v[180:181], v[44:45] op_sel_hi:[1,0,1]
	v_pk_fma_f32 v[138:139], v[138:139], v[180:181], v[46:47] op_sel_hi:[1,0,1]
	v_pk_fma_f32 v[140:141], v[140:141], v[180:181], v[48:49] op_sel_hi:[1,0,1]
	v_cvt_pk_bf16_f32 v168, v142, v143
	v_cvt_pk_bf16_f32 v169, v144, v145
	v_cvt_pk_bf16_f32 v170, v138, v139
	v_cvt_pk_bf16_f32 v171, v140, v141
	global_store_dwordx4 v189, v[168:171], s[80:81]
	v_pk_fma_f32 v[134:135], v[134:135], v[180:181], v[58:59] op_sel_hi:[1,0,1]
	v_pk_fma_f32 v[136:137], v[136:137], v[180:181], v[60:61] op_sel_hi:[1,0,1]
	v_pk_fma_f32 v[130:131], v[130:131], v[180:181], v[62:63] op_sel_hi:[1,0,1]
	v_pk_fma_f32 v[132:133], v[132:133], v[180:181], v[64:65] op_sel_hi:[1,0,1]
	s_nop 0
	v_cvt_pk_bf16_f32 v168, v134, v135
	v_cvt_pk_bf16_f32 v169, v136, v137
	v_cvt_pk_bf16_f32 v170, v130, v131
	v_cvt_pk_bf16_f32 v171, v132, v133
	global_store_dwordx4 v189, v[168:171], s[80:81] offset:256
	s_add_u32 s80, s10, 0x20000
	s_addc_u32 s81, s11, 0
	v_pk_fma_f32 v[126:127], v[126:127], v[188:189], v[42:43] op_sel_hi:[1,0,1]
	v_pk_fma_f32 v[128:129], v[128:129], v[188:189], v[44:45] op_sel_hi:[1,0,1]
	v_pk_fma_f32 v[122:123], v[122:123], v[188:189], v[46:47] op_sel_hi:[1,0,1]
	v_pk_fma_f32 v[124:125], v[124:125], v[188:189], v[48:49] op_sel_hi:[1,0,1]
	v_cvt_pk_bf16_f32 v168, v126, v127
	v_cvt_pk_bf16_f32 v169, v128, v129
	v_cvt_pk_bf16_f32 v170, v122, v123
	v_cvt_pk_bf16_f32 v171, v124, v125
	global_store_dwordx4 v189, v[168:171], s[80:81]
	v_pk_fma_f32 v[118:119], v[118:119], v[188:189], v[58:59] op_sel_hi:[1,0,1]
	v_pk_fma_f32 v[120:121], v[120:121], v[188:189], v[60:61] op_sel_hi:[1,0,1]
	v_pk_fma_f32 v[114:115], v[114:115], v[188:189], v[62:63] op_sel_hi:[1,0,1]
	v_pk_fma_f32 v[116:117], v[116:117], v[188:189], v[64:65] op_sel_hi:[1,0,1]
	s_nop 0
	v_cvt_pk_bf16_f32 v168, v118, v119
	v_cvt_pk_bf16_f32 v169, v120, v121
	v_cvt_pk_bf16_f32 v170, v114, v115
	v_cvt_pk_bf16_f32 v171, v116, v117
	global_store_dwordx4 v189, v[168:171], s[80:81] offset:256
	s_add_u32 s80, s10, 0x40000
	s_addc_u32 s81, s11, 0
	v_pk_fma_f32 v[110:111], v[110:111], v[190:191], v[42:43] op_sel_hi:[1,0,1]
	v_pk_fma_f32 v[112:113], v[112:113], v[190:191], v[44:45] op_sel_hi:[1,0,1]
	v_pk_fma_f32 v[106:107], v[106:107], v[190:191], v[46:47] op_sel_hi:[1,0,1]
	v_pk_fma_f32 v[108:109], v[108:109], v[190:191], v[48:49] op_sel_hi:[1,0,1]
	v_cvt_pk_bf16_f32 v168, v110, v111
	v_cvt_pk_bf16_f32 v169, v112, v113
	v_cvt_pk_bf16_f32 v170, v106, v107
	v_cvt_pk_bf16_f32 v171, v108, v109
	global_store_dwordx4 v189, v[168:171], s[80:81]
	v_pk_fma_f32 v[102:103], v[102:103], v[190:191], v[58:59] op_sel_hi:[1,0,1]
	v_pk_fma_f32 v[104:105], v[104:105], v[190:191], v[60:61] op_sel_hi:[1,0,1]
	v_pk_fma_f32 v[98:99], v[98:99], v[190:191], v[62:63] op_sel_hi:[1,0,1]
	v_pk_fma_f32 v[100:101], v[100:101], v[190:191], v[64:65] op_sel_hi:[1,0,1]
	s_nop 0
	v_cvt_pk_bf16_f32 v168, v102, v103
	v_cvt_pk_bf16_f32 v169, v104, v105
	v_cvt_pk_bf16_f32 v170, v98, v99
	v_cvt_pk_bf16_f32 v171, v100, v101
	global_store_dwordx4 v189, v[168:171], s[80:81] offset:256
	s_add_u32 s80, s10, 0x60000
	s_addc_u32 s81, s11, 0
	v_pk_fma_f32 v[94:95], v[94:95], v[192:193], v[42:43] op_sel_hi:[1,0,1]
	v_pk_fma_f32 v[96:97], v[96:97], v[192:193], v[44:45] op_sel_hi:[1,0,1]
	v_pk_fma_f32 v[90:91], v[90:91], v[192:193], v[46:47] op_sel_hi:[1,0,1]
	v_pk_fma_f32 v[92:93], v[92:93], v[192:193], v[48:49] op_sel_hi:[1,0,1]
	v_cvt_pk_bf16_f32 v168, v94, v95
	v_cvt_pk_bf16_f32 v169, v96, v97
	v_cvt_pk_bf16_f32 v170, v90, v91
	v_cvt_pk_bf16_f32 v171, v92, v93
	global_store_dwordx4 v189, v[168:171], s[80:81]
	v_pk_fma_f32 v[86:87], v[86:87], v[192:193], v[58:59] op_sel_hi:[1,0,1]
	v_pk_fma_f32 v[88:89], v[88:89], v[192:193], v[60:61] op_sel_hi:[1,0,1]
	v_pk_fma_f32 v[82:83], v[82:83], v[192:193], v[62:63] op_sel_hi:[1,0,1]
	v_pk_fma_f32 v[84:85], v[84:85], v[192:193], v[64:65] op_sel_hi:[1,0,1]
	s_nop 0
	v_cvt_pk_bf16_f32 v168, v86, v87
	v_cvt_pk_bf16_f32 v169, v88, v89
	v_cvt_pk_bf16_f32 v170, v82, v83
	v_cvt_pk_bf16_f32 v171, v84, v85
	global_store_dwordx4 v189, v[168:171], s[80:81] offset:256
	s_add_u32 s80, s10, 0x100000
	s_addc_u32 s81, s11, 0
	v_pk_fma_f32 v[78:79], v[78:79], v[194:195], v[42:43] op_sel_hi:[1,0,1]
	v_pk_fma_f32 v[80:81], v[80:81], v[194:195], v[44:45] op_sel_hi:[1,0,1]
	v_pk_fma_f32 v[74:75], v[74:75], v[194:195], v[46:47] op_sel_hi:[1,0,1]
	v_pk_fma_f32 v[76:77], v[76:77], v[194:195], v[48:49] op_sel_hi:[1,0,1]
	v_cvt_pk_bf16_f32 v168, v78, v79
	v_cvt_pk_bf16_f32 v169, v80, v81
	v_cvt_pk_bf16_f32 v170, v74, v75
	v_cvt_pk_bf16_f32 v171, v76, v77
	global_store_dwordx4 v189, v[168:171], s[80:81]
	v_pk_fma_f32 v[70:71], v[70:71], v[194:195], v[58:59] op_sel_hi:[1,0,1]
	v_pk_fma_f32 v[72:73], v[72:73], v[194:195], v[60:61] op_sel_hi:[1,0,1]
	v_pk_fma_f32 v[66:67], v[66:67], v[194:195], v[62:63] op_sel_hi:[1,0,1]
	v_pk_fma_f32 v[68:69], v[68:69], v[194:195], v[64:65] op_sel_hi:[1,0,1]
	s_nop 0
	v_cvt_pk_bf16_f32 v168, v70, v71
	v_cvt_pk_bf16_f32 v169, v72, v73
	v_cvt_pk_bf16_f32 v170, v66, v67
	v_cvt_pk_bf16_f32 v171, v68, v69
	global_store_dwordx4 v189, v[168:171], s[80:81] offset:256
	s_add_u32 s80, s10, 0x120000
	s_addc_u32 s81, s11, 0
	v_pk_fma_f32 v[54:55], v[54:55], v[196:197], v[42:43] op_sel_hi:[1,0,1]
	v_pk_fma_f32 v[56:57], v[56:57], v[196:197], v[44:45] op_sel_hi:[1,0,1]
	v_pk_fma_f32 v[50:51], v[50:51], v[196:197], v[46:47] op_sel_hi:[1,0,1]
	v_pk_fma_f32 v[52:53], v[52:53], v[196:197], v[48:49] op_sel_hi:[1,0,1]
	v_cvt_pk_bf16_f32 v168, v54, v55
	v_cvt_pk_bf16_f32 v169, v56, v57
	v_cvt_pk_bf16_f32 v170, v50, v51
	v_cvt_pk_bf16_f32 v171, v52, v53
	global_store_dwordx4 v189, v[168:171], s[80:81]
	v_pk_fma_f32 v[38:39], v[38:39], v[196:197], v[58:59] op_sel_hi:[1,0,1]
	v_pk_fma_f32 v[40:41], v[40:41], v[196:197], v[60:61] op_sel_hi:[1,0,1]
	v_pk_fma_f32 v[34:35], v[34:35], v[196:197], v[62:63] op_sel_hi:[1,0,1]
	v_pk_fma_f32 v[36:37], v[36:37], v[196:197], v[64:65] op_sel_hi:[1,0,1]
	s_nop 0
	v_cvt_pk_bf16_f32 v168, v38, v39
	v_cvt_pk_bf16_f32 v169, v40, v41
	v_cvt_pk_bf16_f32 v170, v34, v35
	v_cvt_pk_bf16_f32 v171, v36, v37
	global_store_dwordx4 v189, v[168:171], s[80:81] offset:256
	s_add_u32 s80, s10, 0x140000
	s_addc_u32 s81, s11, 0
	v_pk_fma_f32 v[30:31], v[30:31], v[210:211], v[42:43] op_sel_hi:[1,0,1]
	v_pk_fma_f32 v[32:33], v[32:33], v[210:211], v[44:45] op_sel_hi:[1,0,1]
	v_pk_fma_f32 v[26:27], v[26:27], v[210:211], v[46:47] op_sel_hi:[1,0,1]
	v_pk_fma_f32 v[28:29], v[28:29], v[210:211], v[48:49] op_sel_hi:[1,0,1]
	v_cvt_pk_bf16_f32 v168, v30, v31
	v_cvt_pk_bf16_f32 v169, v32, v33
	v_cvt_pk_bf16_f32 v170, v26, v27
	v_cvt_pk_bf16_f32 v171, v28, v29
	global_store_dwordx4 v189, v[168:171], s[80:81]
	v_pk_fma_f32 v[22:23], v[22:23], v[210:211], v[58:59] op_sel_hi:[1,0,1]
	v_pk_fma_f32 v[24:25], v[24:25], v[210:211], v[60:61] op_sel_hi:[1,0,1]
	v_pk_fma_f32 v[18:19], v[18:19], v[210:211], v[62:63] op_sel_hi:[1,0,1]
	v_pk_fma_f32 v[20:21], v[20:21], v[210:211], v[64:65] op_sel_hi:[1,0,1]
	s_nop 0
	v_cvt_pk_bf16_f32 v168, v22, v23
	v_cvt_pk_bf16_f32 v169, v24, v25
	v_cvt_pk_bf16_f32 v170, v18, v19
	v_cvt_pk_bf16_f32 v171, v20, v21
	global_store_dwordx4 v189, v[168:171], s[80:81] offset:256
	s_add_u32 s80, s10, 0x160000
	s_addc_u32 s81, s11, 0
	v_pk_fma_f32 v[14:15], v[14:15], v[212:213], v[42:43] op_sel_hi:[1,0,1]
	v_pk_fma_f32 v[16:17], v[16:17], v[212:213], v[44:45] op_sel_hi:[1,0,1]
	v_pk_fma_f32 v[10:11], v[10:11], v[212:213], v[46:47] op_sel_hi:[1,0,1]
	v_pk_fma_f32 v[12:13], v[12:13], v[212:213], v[48:49] op_sel_hi:[1,0,1]
	v_cvt_pk_bf16_f32 v168, v14, v15
	v_cvt_pk_bf16_f32 v169, v16, v17
	v_cvt_pk_bf16_f32 v170, v10, v11
	v_cvt_pk_bf16_f32 v171, v12, v13
	global_store_dwordx4 v189, v[168:171], s[80:81]
	v_pk_fma_f32 v[6:7], v[6:7], v[212:213], v[58:59] op_sel_hi:[1,0,1]
	v_pk_fma_f32 v[8:9], v[8:9], v[212:213], v[60:61] op_sel_hi:[1,0,1]
	v_pk_fma_f32 v[2:3], v[2:3], v[212:213], v[62:63] op_sel_hi:[1,0,1]
	v_pk_fma_f32 v[4:5], v[4:5], v[212:213], v[64:65] op_sel_hi:[1,0,1]
	s_nop 0
	v_cvt_pk_bf16_f32 v168, v6, v7
	v_cvt_pk_bf16_f32 v169, v8, v9
	v_cvt_pk_bf16_f32 v170, v2, v3
	v_cvt_pk_bf16_f32 v171, v4, v5
	global_store_dwordx4 v189, v[168:171], s[80:81] offset:256
.Lact0_rgin_done:
	s_andn2_b64 vcc, exec, s[14:15]
	s_mov_b64 s[12:13], -1
	s_cbranch_vccnz .LBB0_847
	s_andn2_b64 vcc, exec, s[0:1]
	s_cbranch_vccnz .LBB0_846
	s_barrier
	s_branch .LBB0_846
